# nt on the write-once output stores of the input-projection (P1) epilogue so they do not displace the GEMM operand tiles in L2
# baseline (speedup 1.0000x reference)
; __device__ __forceinline__ unsigned cvt_pk_bf16(float lo, float hi) { unsigned r; asm volatile("v_cvt_pk_bf16_f32 %0, %1, %2" : "=v"(r) : "v"(lo), "v"(hi)); return r; }
;     __device__ __forceinline__ void operator()(const f32x4 (&acc)[2][2][4][2], const pg8::Unit& u, int wr, int wc, int fr, int fq) const {
;     ...
;                         u32x4 w; w.x = cvt_pk_bf16(v0[0], v0[1]); w.y = cvt_pk_bf16(v0[2], v0[3]); w.z = cvt_pk_bf16(v1[0], v1[1]); w.w = cvt_pk_bf16(v1[2], v1[3]);
;                         *(u32x4*)(dst + row * ld + coff + cl) = w;
.LBB0_170:
	s_andn2_b64 vcc, exec, s[6:7]
	s_cbranch_vccnz .LBB0_172
	v_lshlrev_b64 v[158:159], 7, v[156:157]
	v_lshl_add_u64 v[158:159], v[142:143], 0, v[158:159]
	v_cvt_pk_bf16_f32 v162, v124, v125
	v_cvt_pk_bf16_f32 v163, v126, v127
	v_cvt_pk_bf16_f32 v164, v120, v121
	v_cvt_pk_bf16_f32 v165, v122, v123
	global_store_dwordx4 v[158:159], v[162:165], off nt

;     __device__ __forceinline__ void operator()(const f32x4 (&acc)[2][2][4][2], const pg8::Unit& u, int wr, int wc, int fr, int fq) const {
;     ...
;                     } else if (kind == 3) {
;                         float* p = P.CKVF + row * 256 + cl; *(f32x4*)p = v0; *(f32x4*)(p + 4) = v1;
.LBB0_173:
	s_andn2_b64 vcc, exec, s[6:7]
	s_cbranch_vccnz .LBB0_175
	v_lshl_add_u64 v[158:159], v[144:145], 0, v[160:161]
	global_store_dwordx4 v[158:159], v[124:127], off nt
	global_store_dwordx4 v[158:159], v[120:123], off offset:16 nt

; __device__ __forceinline__ unsigned cvt_pk_bf16(float lo, float hi) { unsigned r; asm volatile("v_cvt_pk_bf16_f32 %0, %1, %2" : "=v"(r) : "v"(lo), "v"(hi)); return r; }
;     __device__ __forceinline__ void operator()(const f32x4 (&acc)[2][2][4][2], const pg8::Unit& u, int wr, int wc, int fr, int fq) const {
;     ...
;                         u32x4 w; w.x = cvt_pk_bf16(v0[0], v0[1]); w.y = cvt_pk_bf16(v0[2], v0[3]); w.z = cvt_pk_bf16(v1[0], v1[1]); w.w = cvt_pk_bf16(v1[2], v1[3]);
;                         *(u32x4*)(dst + row * ld + coff + cl) = w;
;                     } else if (kind == 3) {
;                         float* p = P.CKVF + row * 256 + cl; *(f32x4*)p = v0; *(f32x4*)(p + 4) = v1;
.LBB0_183:
	v_lshlrev_b32_e32 v136, 1, v138
	v_lshl_add_u64 v[124:125], v[158:159], 0, v[136:137]
	v_cvt_pk_bf16_f32 v120, v162, v163
	v_cvt_pk_bf16_f32 v121, v164, v165
	v_cvt_pk_bf16_f32 v122, v166, v167
	v_cvt_pk_bf16_f32 v123, v168, v169
	global_store_dwordx4 v[124:125], v[120:123], off nt
.LBB0_184:
	s_nop 1
	v_cndmask_b32_e64 v120, 0, 1, s[70:71]
	v_cmp_ne_u32_e64 s[8:9], 1, v120
	v_cndmask_b32_e64 v120, 0, 1, s[10:11]
	s_mov_b64 s[44:45], -1
	s_andn2_b64 vcc, exec, s[70:71]
	v_cmp_ne_u32_e64 s[6:7], 1, v120
	s_cbranch_vccnz .LBB0_188
	s_and_b64 vcc, exec, s[6:7]
	s_cbranch_vccnz .LBB0_187
	v_lshl_add_u64 v[120:121], v[146:147], 0, v[160:161]
	global_store_dwordx4 v[120:121], v[116:119], off nt
	global_store_dwordx4 v[120:121], v[112:115], off offset:16 nt

; __device__ __forceinline__ unsigned cvt_pk_bf16(float lo, float hi) { unsigned r; asm volatile("v_cvt_pk_bf16_f32 %0, %1, %2" : "=v"(r) : "v"(lo), "v"(hi)); return r; }
;     __device__ __forceinline__ void operator()(const f32x4 (&acc)[2][2][4][2], const pg8::Unit& u, int wr, int wc, int fr, int fq) const {
;     ...
;                         u32x4 w; w.x = cvt_pk_bf16(v0[0], v0[1]); w.y = cvt_pk_bf16(v0[2], v0[3]); w.z = cvt_pk_bf16(v1[0], v1[1]); w.w = cvt_pk_bf16(v1[2], v1[3]);
;                         *(u32x4*)(dst + row * ld + coff + cl) = w;
.LBB0_195:
	v_lshlrev_b32_e32 v136, 1, v138
	v_lshl_add_u64 v[116:117], v[158:159], 0, v[136:137]
	v_cvt_pk_bf16_f32 v112, v120, v121
	v_cvt_pk_bf16_f32 v113, v122, v123
	v_cvt_pk_bf16_f32 v114, v124, v125
	v_cvt_pk_bf16_f32 v115, v126, v127
	global_store_dwordx4 v[116:117], v[112:115], off offset:256 nt

; __device__ __forceinline__ unsigned cvt_pk_bf16(float lo, float hi) { unsigned r; asm volatile("v_cvt_pk_bf16_f32 %0, %1, %2" : "=v"(r) : "v"(lo), "v"(hi)); return r; }
;     __device__ __forceinline__ void operator()(const f32x4 (&acc)[2][2][4][2], const pg8::Unit& u, int wr, int wc, int fr, int fq) const {
;     ...
;                         if (cl < 64) { u32x4 w; w.x = cvt_pk_bf16(v0[0], v0[1]); w.y = cvt_pk_bf16(v0[2], v0[3]); w.z = cvt_pk_bf16(v1[0], v1[1]); w.w = cvt_pk_bf16(v1[2], v1[3]);
;                             *(u32x4*)(P.KI + row * 64 + cl) = w; }
.LBB0_202:
	s_andn2_b64 vcc, exec, s[44:45]
	s_cbranch_vccnz .LBB0_204
	v_lshlrev_b64 v[120:121], 7, v[112:113]
	v_lshl_add_u64 v[120:121], v[142:143], 0, v[120:121]
	v_cvt_pk_bf16_f32 v116, v108, v109
	v_cvt_pk_bf16_f32 v117, v110, v111
	v_cvt_pk_bf16_f32 v118, v104, v105
	v_cvt_pk_bf16_f32 v119, v106, v107
	global_store_dwordx4 v[120:121], v[116:119], off nt

;     __device__ __forceinline__ void operator()(const f32x4 (&acc)[2][2][4][2], const pg8::Unit& u, int wr, int wc, int fr, int fq) const {
;     ...
;                         else if (cl < 80) { float* p = P.WI + row * 16 + (cl - 64); *(f32x4*)p = v0; *(f32x4*)(p + 4) = v1; }
.LBB0_205:
	s_andn2_b64 vcc, exec, s[44:45]
	s_cbranch_vccnz .LBB0_207
	v_lshl_add_u64 v[116:117], v[144:145], 0, v[114:115]
	global_store_dwordx4 v[116:117], v[108:111], off nt
	global_store_dwordx4 v[116:117], v[104:107], off offset:16 nt

; __device__ __forceinline__ unsigned cvt_pk_bf16(float lo, float hi) { unsigned r; asm volatile("v_cvt_pk_bf16_f32 %0, %1, %2" : "=v"(r) : "v"(lo), "v"(hi)); return r; }
;     __device__ __forceinline__ void operator()(const f32x4 (&acc)[2][2][4][2], const pg8::Unit& u, int wr, int wc, int fr, int fq) const {
;     ...
;                         u32x4 w; w.x = cvt_pk_bf16(v0[0], v0[1]); w.y = cvt_pk_bf16(v0[2], v0[3]); w.z = cvt_pk_bf16(v1[0], v1[1]); w.w = cvt_pk_bf16(v1[2], v1[3]);
;                         *(u32x4*)(dst + row * ld + coff + cl) = w;
.LBB0_215:
	v_lshlrev_b32_e32 v136, 1, v138
	v_lshl_add_u64 v[108:109], v[112:113], 0, v[136:137]
	v_cvt_pk_bf16_f32 v104, v116, v117
	v_cvt_pk_bf16_f32 v105, v118, v119
	v_cvt_pk_bf16_f32 v106, v120, v121
	v_cvt_pk_bf16_f32 v107, v122, v123
	global_store_dwordx4 v[108:109], v[104:107], off nt
	s_and_b64 vcc, exec, s[8:9]
	s_mov_b64 s[44:45], -1
	s_cbranch_vccz .LBB0_218

;     __device__ __forceinline__ void operator()(const f32x4 (&acc)[2][2][4][2], const pg8::Unit& u, int wr, int wc, int fr, int fq) const {
;     ...
;                         float* p = P.CKVF + row * 256 + cl; *(f32x4*)p = v0; *(f32x4*)(p + 4) = v1;
.LBB0_218:
	s_and_b64 vcc, exec, s[6:7]
	s_cbranch_vccnz .LBB0_220
	v_lshl_add_u64 v[104:105], v[146:147], 0, v[114:115]
	global_store_dwordx4 v[104:105], v[100:103], off nt
	global_store_dwordx4 v[104:105], v[96:99], off offset:16 nt

; __device__ __forceinline__ unsigned cvt_pk_bf16(float lo, float hi) { unsigned r; asm volatile("v_cvt_pk_bf16_f32 %0, %1, %2" : "=v"(r) : "v"(lo), "v"(hi)); return r; }
;     __device__ __forceinline__ void operator()(const f32x4 (&acc)[2][2][4][2], const pg8::Unit& u, int wr, int wc, int fr, int fq) const {
;     ...
;                         u32x4 w; w.x = cvt_pk_bf16(v0[0], v0[1]); w.y = cvt_pk_bf16(v0[2], v0[3]); w.z = cvt_pk_bf16(v1[0], v1[1]); w.w = cvt_pk_bf16(v1[2], v1[3]);
;                         *(u32x4*)(dst + row * ld + coff + cl) = w;
.LBB0_227:
	v_lshlrev_b32_e32 v136, 1, v138
	v_lshl_add_u64 v[100:101], v[112:113], 0, v[136:137]
	v_cvt_pk_bf16_f32 v96, v104, v105
	v_cvt_pk_bf16_f32 v97, v106, v107
	v_cvt_pk_bf16_f32 v98, v108, v109
	v_cvt_pk_bf16_f32 v99, v110, v111
	global_store_dwordx4 v[100:101], v[96:99], off offset:256 nt

; __device__ __forceinline__ unsigned cvt_pk_bf16(float lo, float hi) { unsigned r; asm volatile("v_cvt_pk_bf16_f32 %0, %1, %2" : "=v"(r) : "v"(lo), "v"(hi)); return r; }
;     __device__ __forceinline__ void operator()(const f32x4 (&acc)[2][2][4][2], const pg8::Unit& u, int wr, int wc, int fr, int fq) const {
;     ...
;                         if (cl < 64) { u32x4 w; w.x = cvt_pk_bf16(v0[0], v0[1]); w.y = cvt_pk_bf16(v0[2], v0[3]); w.z = cvt_pk_bf16(v1[0], v1[1]); w.w = cvt_pk_bf16(v1[2], v1[3]);
;                             *(u32x4*)(P.KI + row * 64 + cl) = w; }
.LBB0_234:
	s_andn2_b64 vcc, exec, s[44:45]
	s_cbranch_vccnz .LBB0_236
	v_lshlrev_b64 v[104:105], 7, v[96:97]
	v_lshl_add_u64 v[104:105], v[142:143], 0, v[104:105]
	v_cvt_pk_bf16_f32 v100, v92, v93
	v_cvt_pk_bf16_f32 v101, v94, v95
	v_cvt_pk_bf16_f32 v102, v88, v89
	v_cvt_pk_bf16_f32 v103, v90, v91
	global_store_dwordx4 v[104:105], v[100:103], off nt

;     __device__ __forceinline__ void operator()(const f32x4 (&acc)[2][2][4][2], const pg8::Unit& u, int wr, int wc, int fr, int fq) const {
;     ...
;                         else if (cl < 80) { float* p = P.WI + row * 16 + (cl - 64); *(f32x4*)p = v0; *(f32x4*)(p + 4) = v1; }
.LBB0_237:
	s_andn2_b64 vcc, exec, s[44:45]
	s_cbranch_vccnz .LBB0_239
	v_lshl_add_u64 v[100:101], v[144:145], 0, v[98:99]
	global_store_dwordx4 v[100:101], v[92:95], off nt
	global_store_dwordx4 v[100:101], v[88:91], off offset:16 nt

; __device__ __forceinline__ unsigned cvt_pk_bf16(float lo, float hi) { unsigned r; asm volatile("v_cvt_pk_bf16_f32 %0, %1, %2" : "=v"(r) : "v"(lo), "v"(hi)); return r; }
;     __device__ __forceinline__ void operator()(const f32x4 (&acc)[2][2][4][2], const pg8::Unit& u, int wr, int wc, int fr, int fq) const {
;     ...
;                         u32x4 w; w.x = cvt_pk_bf16(v0[0], v0[1]); w.y = cvt_pk_bf16(v0[2], v0[3]); w.z = cvt_pk_bf16(v1[0], v1[1]); w.w = cvt_pk_bf16(v1[2], v1[3]);
;                         *(u32x4*)(dst + row * ld + coff + cl) = w;
.LBB0_247:
	v_lshlrev_b32_e32 v136, 1, v138
	v_lshl_add_u64 v[92:93], v[96:97], 0, v[136:137]
	v_cvt_pk_bf16_f32 v88, v100, v101
	v_cvt_pk_bf16_f32 v89, v102, v103
	v_cvt_pk_bf16_f32 v90, v104, v105
	v_cvt_pk_bf16_f32 v91, v106, v107
	global_store_dwordx4 v[92:93], v[88:91], off nt
	s_and_b64 vcc, exec, s[8:9]
	s_mov_b64 s[44:45], -1
	s_cbranch_vccz .LBB0_250

;     __device__ __forceinline__ void operator()(const f32x4 (&acc)[2][2][4][2], const pg8::Unit& u, int wr, int wc, int fr, int fq) const {
;     ...
;                         float* p = P.CKVF + row * 256 + cl; *(f32x4*)p = v0; *(f32x4*)(p + 4) = v1;
.LBB0_250:
	s_and_b64 vcc, exec, s[6:7]
	s_cbranch_vccnz .LBB0_252
	v_lshl_add_u64 v[88:89], v[146:147], 0, v[98:99]
	global_store_dwordx4 v[88:89], v[84:87], off nt
	global_store_dwordx4 v[88:89], v[80:83], off offset:16 nt

; __device__ __forceinline__ unsigned cvt_pk_bf16(float lo, float hi) { unsigned r; asm volatile("v_cvt_pk_bf16_f32 %0, %1, %2" : "=v"(r) : "v"(lo), "v"(hi)); return r; }
;     __device__ __forceinline__ void operator()(const f32x4 (&acc)[2][2][4][2], const pg8::Unit& u, int wr, int wc, int fr, int fq) const {
;     ...
;                         u32x4 w; w.x = cvt_pk_bf16(v0[0], v0[1]); w.y = cvt_pk_bf16(v0[2], v0[3]); w.z = cvt_pk_bf16(v1[0], v1[1]); w.w = cvt_pk_bf16(v1[2], v1[3]);
;                         *(u32x4*)(dst + row * ld + coff + cl) = w;
.LBB0_259:
	v_lshlrev_b32_e32 v136, 1, v138
	v_lshl_add_u64 v[84:85], v[96:97], 0, v[136:137]
	v_cvt_pk_bf16_f32 v80, v88, v89
	v_cvt_pk_bf16_f32 v81, v90, v91
	v_cvt_pk_bf16_f32 v82, v92, v93
	v_cvt_pk_bf16_f32 v83, v94, v95
	global_store_dwordx4 v[84:85], v[80:83], off offset:256 nt

; __device__ __forceinline__ unsigned cvt_pk_bf16(float lo, float hi) { unsigned r; asm volatile("v_cvt_pk_bf16_f32 %0, %1, %2" : "=v"(r) : "v"(lo), "v"(hi)); return r; }
;     __device__ __forceinline__ void operator()(const f32x4 (&acc)[2][2][4][2], const pg8::Unit& u, int wr, int wc, int fr, int fq) const {
;     ...
;                         if (cl < 64) { u32x4 w; w.x = cvt_pk_bf16(v0[0], v0[1]); w.y = cvt_pk_bf16(v0[2], v0[3]); w.z = cvt_pk_bf16(v1[0], v1[1]); w.w = cvt_pk_bf16(v1[2], v1[3]);
;                             *(u32x4*)(P.KI + row * 64 + cl) = w; }
.LBB0_266:
	s_andn2_b64 vcc, exec, s[44:45]
	s_cbranch_vccnz .LBB0_268
	v_lshlrev_b64 v[88:89], 7, v[80:81]
	v_lshl_add_u64 v[88:89], v[142:143], 0, v[88:89]
	v_cvt_pk_bf16_f32 v84, v76, v77
	v_cvt_pk_bf16_f32 v85, v78, v79
	v_cvt_pk_bf16_f32 v86, v72, v73
	v_cvt_pk_bf16_f32 v87, v74, v75
	global_store_dwordx4 v[88:89], v[84:87], off nt

;     __device__ __forceinline__ void operator()(const f32x4 (&acc)[2][2][4][2], const pg8::Unit& u, int wr, int wc, int fr, int fq) const {
;     ...
;                         else if (cl < 80) { float* p = P.WI + row * 16 + (cl - 64); *(f32x4*)p = v0; *(f32x4*)(p + 4) = v1; }
.LBB0_269:
	s_andn2_b64 vcc, exec, s[44:45]
	s_cbranch_vccnz .LBB0_271
	v_lshl_add_u64 v[84:85], v[144:145], 0, v[82:83]
	global_store_dwordx4 v[84:85], v[76:79], off nt
	global_store_dwordx4 v[84:85], v[72:75], off offset:16 nt

; __device__ __forceinline__ unsigned cvt_pk_bf16(float lo, float hi) { unsigned r; asm volatile("v_cvt_pk_bf16_f32 %0, %1, %2" : "=v"(r) : "v"(lo), "v"(hi)); return r; }
;     __device__ __forceinline__ void operator()(const f32x4 (&acc)[2][2][4][2], const pg8::Unit& u, int wr, int wc, int fr, int fq) const {
;     ...
;                         u32x4 w; w.x = cvt_pk_bf16(v0[0], v0[1]); w.y = cvt_pk_bf16(v0[2], v0[3]); w.z = cvt_pk_bf16(v1[0], v1[1]); w.w = cvt_pk_bf16(v1[2], v1[3]);
;                         *(u32x4*)(dst + row * ld + coff + cl) = w;
.LBB0_279:
	v_lshlrev_b32_e32 v136, 1, v138
	v_lshl_add_u64 v[76:77], v[80:81], 0, v[136:137]
	v_cvt_pk_bf16_f32 v72, v84, v85
	v_cvt_pk_bf16_f32 v73, v86, v87
	v_cvt_pk_bf16_f32 v74, v88, v89
	v_cvt_pk_bf16_f32 v75, v90, v91
	global_store_dwordx4 v[76:77], v[72:75], off nt
	s_and_b64 vcc, exec, s[8:9]
	s_mov_b64 s[44:45], -1
	s_cbranch_vccz .LBB0_282

;     __device__ __forceinline__ void operator()(const f32x4 (&acc)[2][2][4][2], const pg8::Unit& u, int wr, int wc, int fr, int fq) const {
;     ...
;                         float* p = P.CKVF + row * 256 + cl; *(f32x4*)p = v0; *(f32x4*)(p + 4) = v1;
.LBB0_282:
	s_and_b64 vcc, exec, s[6:7]
	s_cbranch_vccnz .LBB0_284
	v_lshl_add_u64 v[72:73], v[146:147], 0, v[82:83]
	global_store_dwordx4 v[72:73], v[68:71], off nt
	global_store_dwordx4 v[72:73], v[64:67], off offset:16 nt

; __device__ __forceinline__ unsigned cvt_pk_bf16(float lo, float hi) { unsigned r; asm volatile("v_cvt_pk_bf16_f32 %0, %1, %2" : "=v"(r) : "v"(lo), "v"(hi)); return r; }
;     __device__ __forceinline__ void operator()(const f32x4 (&acc)[2][2][4][2], const pg8::Unit& u, int wr, int wc, int fr, int fq) const {
;     ...
;                         u32x4 w; w.x = cvt_pk_bf16(v0[0], v0[1]); w.y = cvt_pk_bf16(v0[2], v0[3]); w.z = cvt_pk_bf16(v1[0], v1[1]); w.w = cvt_pk_bf16(v1[2], v1[3]);
;                         *(u32x4*)(dst + row * ld + coff + cl) = w;
.LBB0_291:
	v_lshlrev_b32_e32 v136, 1, v138
	v_lshl_add_u64 v[68:69], v[80:81], 0, v[136:137]
	v_cvt_pk_bf16_f32 v64, v72, v73
	v_cvt_pk_bf16_f32 v65, v74, v75
	v_cvt_pk_bf16_f32 v66, v76, v77
	v_cvt_pk_bf16_f32 v67, v78, v79
	global_store_dwordx4 v[68:69], v[64:67], off offset:256 nt

; __device__ __forceinline__ unsigned cvt_pk_bf16(float lo, float hi) { unsigned r; asm volatile("v_cvt_pk_bf16_f32 %0, %1, %2" : "=v"(r) : "v"(lo), "v"(hi)); return r; }
;     __device__ __forceinline__ void operator()(const f32x4 (&acc)[2][2][4][2], const pg8::Unit& u, int wr, int wc, int fr, int fq) const {
;     ...
;                         if (cl < 64) { u32x4 w; w.x = cvt_pk_bf16(v0[0], v0[1]); w.y = cvt_pk_bf16(v0[2], v0[3]); w.z = cvt_pk_bf16(v1[0], v1[1]); w.w = cvt_pk_bf16(v1[2], v1[3]);
;                             *(u32x4*)(P.KI + row * 64 + cl) = w; }
.LBB0_298:
	s_andn2_b64 vcc, exec, s[44:45]
	s_cbranch_vccnz .LBB0_300
	v_lshlrev_b64 v[72:73], 7, v[64:65]
	v_lshl_add_u64 v[72:73], v[142:143], 0, v[72:73]
	v_cvt_pk_bf16_f32 v68, v60, v61
	v_cvt_pk_bf16_f32 v69, v62, v63
	v_cvt_pk_bf16_f32 v70, v56, v57
	v_cvt_pk_bf16_f32 v71, v58, v59
	global_store_dwordx4 v[72:73], v[68:71], off nt

;     __device__ __forceinline__ void operator()(const f32x4 (&acc)[2][2][4][2], const pg8::Unit& u, int wr, int wc, int fr, int fq) const {
;     ...
;                         else if (cl < 80) { float* p = P.WI + row * 16 + (cl - 64); *(f32x4*)p = v0; *(f32x4*)(p + 4) = v1; }
.LBB0_301:
	s_andn2_b64 vcc, exec, s[44:45]
	s_cbranch_vccnz .LBB0_303
	v_lshl_add_u64 v[68:69], v[144:145], 0, v[66:67]
	global_store_dwordx4 v[68:69], v[60:63], off nt
	global_store_dwordx4 v[68:69], v[56:59], off offset:16 nt

; __device__ __forceinline__ unsigned cvt_pk_bf16(float lo, float hi) { unsigned r; asm volatile("v_cvt_pk_bf16_f32 %0, %1, %2" : "=v"(r) : "v"(lo), "v"(hi)); return r; }
;     __device__ __forceinline__ void operator()(const f32x4 (&acc)[2][2][4][2], const pg8::Unit& u, int wr, int wc, int fr, int fq) const {
;     ...
;                         u32x4 w; w.x = cvt_pk_bf16(v0[0], v0[1]); w.y = cvt_pk_bf16(v0[2], v0[3]); w.z = cvt_pk_bf16(v1[0], v1[1]); w.w = cvt_pk_bf16(v1[2], v1[3]);
;                         *(u32x4*)(dst + row * ld + coff + cl) = w;
.LBB0_311:
	v_lshlrev_b32_e32 v136, 1, v138
	v_lshl_add_u64 v[60:61], v[64:65], 0, v[136:137]
	v_cvt_pk_bf16_f32 v56, v68, v69
	v_cvt_pk_bf16_f32 v57, v70, v71
	v_cvt_pk_bf16_f32 v58, v72, v73
	v_cvt_pk_bf16_f32 v59, v74, v75
	global_store_dwordx4 v[60:61], v[56:59], off nt
	s_and_b64 vcc, exec, s[8:9]
	s_mov_b64 s[44:45], -1
	s_cbranch_vccz .LBB0_314

;     __device__ __forceinline__ void operator()(const f32x4 (&acc)[2][2][4][2], const pg8::Unit& u, int wr, int wc, int fr, int fq) const {
;     ...
;                         float* p = P.CKVF + row * 256 + cl; *(f32x4*)p = v0; *(f32x4*)(p + 4) = v1;
.LBB0_314:
	s_and_b64 vcc, exec, s[6:7]
	s_cbranch_vccnz .LBB0_316
	v_lshl_add_u64 v[56:57], v[146:147], 0, v[66:67]
	global_store_dwordx4 v[56:57], v[52:55], off nt
	global_store_dwordx4 v[56:57], v[48:51], off offset:16 nt

; __device__ __forceinline__ unsigned cvt_pk_bf16(float lo, float hi) { unsigned r; asm volatile("v_cvt_pk_bf16_f32 %0, %1, %2" : "=v"(r) : "v"(lo), "v"(hi)); return r; }
;     __device__ __forceinline__ void operator()(const f32x4 (&acc)[2][2][4][2], const pg8::Unit& u, int wr, int wc, int fr, int fq) const {
;     ...
;                         u32x4 w; w.x = cvt_pk_bf16(v0[0], v0[1]); w.y = cvt_pk_bf16(v0[2], v0[3]); w.z = cvt_pk_bf16(v1[0], v1[1]); w.w = cvt_pk_bf16(v1[2], v1[3]);
;                         *(u32x4*)(dst + row * ld + coff + cl) = w;
.LBB0_323:
	v_lshlrev_b32_e32 v136, 1, v138
	v_lshl_add_u64 v[52:53], v[64:65], 0, v[136:137]
	v_cvt_pk_bf16_f32 v48, v56, v57
	v_cvt_pk_bf16_f32 v49, v58, v59
	v_cvt_pk_bf16_f32 v50, v60, v61
	v_cvt_pk_bf16_f32 v51, v62, v63
	global_store_dwordx4 v[52:53], v[48:51], off offset:256 nt

; __device__ __forceinline__ unsigned cvt_pk_bf16(float lo, float hi) { unsigned r; asm volatile("v_cvt_pk_bf16_f32 %0, %1, %2" : "=v"(r) : "v"(lo), "v"(hi)); return r; }
;     __device__ __forceinline__ void operator()(const f32x4 (&acc)[2][2][4][2], const pg8::Unit& u, int wr, int wc, int fr, int fq) const {
;     ...
;                         if (cl < 64) { u32x4 w; w.x = cvt_pk_bf16(v0[0], v0[1]); w.y = cvt_pk_bf16(v0[2], v0[3]); w.z = cvt_pk_bf16(v1[0], v1[1]); w.w = cvt_pk_bf16(v1[2], v1[3]);
;                             *(u32x4*)(P.KI + row * 64 + cl) = w; }
.LBB0_330:
	s_andn2_b64 vcc, exec, s[44:45]
	s_cbranch_vccnz .LBB0_332
	v_lshlrev_b64 v[56:57], 7, v[48:49]
	v_lshl_add_u64 v[56:57], v[142:143], 0, v[56:57]
	v_cvt_pk_bf16_f32 v52, v44, v45
	v_cvt_pk_bf16_f32 v53, v46, v47
	v_cvt_pk_bf16_f32 v54, v40, v41
	v_cvt_pk_bf16_f32 v55, v42, v43
	global_store_dwordx4 v[56:57], v[52:55], off nt

;     __device__ __forceinline__ void operator()(const f32x4 (&acc)[2][2][4][2], const pg8::Unit& u, int wr, int wc, int fr, int fq) const {
;     ...
;                         else if (cl < 80) { float* p = P.WI + row * 16 + (cl - 64); *(f32x4*)p = v0; *(f32x4*)(p + 4) = v1; }
.LBB0_333:
	s_andn2_b64 vcc, exec, s[44:45]
	s_cbranch_vccnz .LBB0_335
	v_lshl_add_u64 v[52:53], v[144:145], 0, v[50:51]
	global_store_dwordx4 v[52:53], v[44:47], off nt
	global_store_dwordx4 v[52:53], v[40:43], off offset:16 nt

; __device__ __forceinline__ unsigned cvt_pk_bf16(float lo, float hi) { unsigned r; asm volatile("v_cvt_pk_bf16_f32 %0, %1, %2" : "=v"(r) : "v"(lo), "v"(hi)); return r; }
;     __device__ __forceinline__ void operator()(const f32x4 (&acc)[2][2][4][2], const pg8::Unit& u, int wr, int wc, int fr, int fq) const {
;     ...
;                         u32x4 w; w.x = cvt_pk_bf16(v0[0], v0[1]); w.y = cvt_pk_bf16(v0[2], v0[3]); w.z = cvt_pk_bf16(v1[0], v1[1]); w.w = cvt_pk_bf16(v1[2], v1[3]);
;                         *(u32x4*)(dst + row * ld + coff + cl) = w;
.LBB0_343:
	v_lshlrev_b32_e32 v136, 1, v138
	v_lshl_add_u64 v[44:45], v[48:49], 0, v[136:137]
	v_cvt_pk_bf16_f32 v40, v52, v53
	v_cvt_pk_bf16_f32 v41, v54, v55
	v_cvt_pk_bf16_f32 v42, v56, v57
	v_cvt_pk_bf16_f32 v43, v58, v59
	global_store_dwordx4 v[44:45], v[40:43], off nt
	s_and_b64 vcc, exec, s[8:9]
	s_mov_b64 s[44:45], -1
	s_cbranch_vccz .LBB0_346

;     __device__ __forceinline__ void operator()(const f32x4 (&acc)[2][2][4][2], const pg8::Unit& u, int wr, int wc, int fr, int fq) const {
;     ...
;                         float* p = P.CKVF + row * 256 + cl; *(f32x4*)p = v0; *(f32x4*)(p + 4) = v1;
.LBB0_346:
	s_and_b64 vcc, exec, s[6:7]
	s_cbranch_vccnz .LBB0_348
	v_lshl_add_u64 v[40:41], v[146:147], 0, v[50:51]
	global_store_dwordx4 v[40:41], v[36:39], off nt
	global_store_dwordx4 v[40:41], v[32:35], off offset:16 nt

; __device__ __forceinline__ unsigned cvt_pk_bf16(float lo, float hi) { unsigned r; asm volatile("v_cvt_pk_bf16_f32 %0, %1, %2" : "=v"(r) : "v"(lo), "v"(hi)); return r; }
;     __device__ __forceinline__ void operator()(const f32x4 (&acc)[2][2][4][2], const pg8::Unit& u, int wr, int wc, int fr, int fq) const {
;     ...
;                         u32x4 w; w.x = cvt_pk_bf16(v0[0], v0[1]); w.y = cvt_pk_bf16(v0[2], v0[3]); w.z = cvt_pk_bf16(v1[0], v1[1]); w.w = cvt_pk_bf16(v1[2], v1[3]);
;                         *(u32x4*)(dst + row * ld + coff + cl) = w;
.LBB0_355:
	v_lshlrev_b32_e32 v136, 1, v138
	v_lshl_add_u64 v[36:37], v[48:49], 0, v[136:137]
	v_cvt_pk_bf16_f32 v32, v40, v41
	v_cvt_pk_bf16_f32 v33, v42, v43
	v_cvt_pk_bf16_f32 v34, v44, v45
	v_cvt_pk_bf16_f32 v35, v46, v47
	global_store_dwordx4 v[36:37], v[32:35], off offset:256 nt

; __device__ __forceinline__ unsigned cvt_pk_bf16(float lo, float hi) { unsigned r; asm volatile("v_cvt_pk_bf16_f32 %0, %1, %2" : "=v"(r) : "v"(lo), "v"(hi)); return r; }
;     __device__ __forceinline__ void operator()(const f32x4 (&acc)[2][2][4][2], const pg8::Unit& u, int wr, int wc, int fr, int fq) const {
;     ...
;                         if (cl < 64) { u32x4 w; w.x = cvt_pk_bf16(v0[0], v0[1]); w.y = cvt_pk_bf16(v0[2], v0[3]); w.z = cvt_pk_bf16(v1[0], v1[1]); w.w = cvt_pk_bf16(v1[2], v1[3]);
;                             *(u32x4*)(P.KI + row * 64 + cl) = w; }
.LBB0_362:
	s_andn2_b64 vcc, exec, s[44:45]
	s_cbranch_vccnz .LBB0_364
	v_lshlrev_b64 v[40:41], 7, v[32:33]
	v_lshl_add_u64 v[40:41], v[142:143], 0, v[40:41]
	v_cvt_pk_bf16_f32 v36, v28, v29
	v_cvt_pk_bf16_f32 v37, v30, v31
	v_cvt_pk_bf16_f32 v38, v24, v25
	v_cvt_pk_bf16_f32 v39, v26, v27
	global_store_dwordx4 v[40:41], v[36:39], off nt

;     __device__ __forceinline__ void operator()(const f32x4 (&acc)[2][2][4][2], const pg8::Unit& u, int wr, int wc, int fr, int fq) const {
;     ...
;                         else if (cl < 80) { float* p = P.WI + row * 16 + (cl - 64); *(f32x4*)p = v0; *(f32x4*)(p + 4) = v1; }
.LBB0_365:
	s_andn2_b64 vcc, exec, s[44:45]
	s_cbranch_vccnz .LBB0_367
	v_lshl_add_u64 v[36:37], v[144:145], 0, v[34:35]
	global_store_dwordx4 v[36:37], v[28:31], off nt
	global_store_dwordx4 v[36:37], v[24:27], off offset:16 nt

; __device__ __forceinline__ unsigned cvt_pk_bf16(float lo, float hi) { unsigned r; asm volatile("v_cvt_pk_bf16_f32 %0, %1, %2" : "=v"(r) : "v"(lo), "v"(hi)); return r; }
;     __device__ __forceinline__ void operator()(const f32x4 (&acc)[2][2][4][2], const pg8::Unit& u, int wr, int wc, int fr, int fq) const {
;     ...
;                         u32x4 w; w.x = cvt_pk_bf16(v0[0], v0[1]); w.y = cvt_pk_bf16(v0[2], v0[3]); w.z = cvt_pk_bf16(v1[0], v1[1]); w.w = cvt_pk_bf16(v1[2], v1[3]);
;                         *(u32x4*)(dst + row * ld + coff + cl) = w;
.LBB0_375:
	v_lshlrev_b32_e32 v136, 1, v138
	v_lshl_add_u64 v[28:29], v[32:33], 0, v[136:137]
	v_cvt_pk_bf16_f32 v24, v36, v37
	v_cvt_pk_bf16_f32 v25, v38, v39
	v_cvt_pk_bf16_f32 v26, v40, v41
	v_cvt_pk_bf16_f32 v27, v42, v43
	global_store_dwordx4 v[28:29], v[24:27], off nt
	s_and_b64 vcc, exec, s[8:9]
	s_mov_b64 s[44:45], -1
	s_cbranch_vccz .LBB0_378

;     __device__ __forceinline__ void operator()(const f32x4 (&acc)[2][2][4][2], const pg8::Unit& u, int wr, int wc, int fr, int fq) const {
;     ...
;                         float* p = P.CKVF + row * 256 + cl; *(f32x4*)p = v0; *(f32x4*)(p + 4) = v1;
.LBB0_378:
	s_and_b64 vcc, exec, s[6:7]
	s_cbranch_vccnz .LBB0_380
	v_lshl_add_u64 v[24:25], v[146:147], 0, v[34:35]
	global_store_dwordx4 v[24:25], v[20:23], off nt
	global_store_dwordx4 v[24:25], v[16:19], off offset:16 nt

; __device__ __forceinline__ unsigned cvt_pk_bf16(float lo, float hi) { unsigned r; asm volatile("v_cvt_pk_bf16_f32 %0, %1, %2" : "=v"(r) : "v"(lo), "v"(hi)); return r; }
;     __device__ __forceinline__ void operator()(const f32x4 (&acc)[2][2][4][2], const pg8::Unit& u, int wr, int wc, int fr, int fq) const {
;     ...
;                         u32x4 w; w.x = cvt_pk_bf16(v0[0], v0[1]); w.y = cvt_pk_bf16(v0[2], v0[3]); w.z = cvt_pk_bf16(v1[0], v1[1]); w.w = cvt_pk_bf16(v1[2], v1[3]);
;                         *(u32x4*)(dst + row * ld + coff + cl) = w;
.LBB0_387:
	v_lshlrev_b32_e32 v136, 1, v138
	v_lshl_add_u64 v[20:21], v[32:33], 0, v[136:137]
	v_cvt_pk_bf16_f32 v16, v24, v25
	v_cvt_pk_bf16_f32 v17, v26, v27
	v_cvt_pk_bf16_f32 v18, v28, v29
	v_cvt_pk_bf16_f32 v19, v30, v31
	global_store_dwordx4 v[20:21], v[16:19], off offset:256 nt

; __device__ __forceinline__ unsigned cvt_pk_bf16(float lo, float hi) { unsigned r; asm volatile("v_cvt_pk_bf16_f32 %0, %1, %2" : "=v"(r) : "v"(lo), "v"(hi)); return r; }
;     __device__ __forceinline__ void operator()(const f32x4 (&acc)[2][2][4][2], const pg8::Unit& u, int wr, int wc, int fr, int fq) const {
;     ...
;                         if (cl < 64) { u32x4 w; w.x = cvt_pk_bf16(v0[0], v0[1]); w.y = cvt_pk_bf16(v0[2], v0[3]); w.z = cvt_pk_bf16(v1[0], v1[1]); w.w = cvt_pk_bf16(v1[2], v1[3]);
;                             *(u32x4*)(P.KI + row * 64 + cl) = w; }
.LBB0_394:
	s_andn2_b64 vcc, exec, s[12:13]
	s_cbranch_vccnz .LBB0_396
	v_lshlrev_b64 v[24:25], 7, v[16:17]
	v_lshl_add_u64 v[24:25], v[142:143], 0, v[24:25]
	v_cvt_pk_bf16_f32 v20, v12, v13
	v_cvt_pk_bf16_f32 v21, v14, v15
	v_cvt_pk_bf16_f32 v22, v8, v9
	v_cvt_pk_bf16_f32 v23, v10, v11
	global_store_dwordx4 v[24:25], v[20:23], off nt

;     __device__ __forceinline__ void operator()(const f32x4 (&acc)[2][2][4][2], const pg8::Unit& u, int wr, int wc, int fr, int fq) const {
;     ...
;                         else if (cl < 80) { float* p = P.WI + row * 16 + (cl - 64); *(f32x4*)p = v0; *(f32x4*)(p + 4) = v1; }
.LBB0_397:
	s_andn2_b64 vcc, exec, s[12:13]
	s_cbranch_vccnz .LBB0_399
	v_lshl_add_u64 v[20:21], v[144:145], 0, v[18:19]
	global_store_dwordx4 v[20:21], v[12:15], off nt
	global_store_dwordx4 v[20:21], v[8:11], off offset:16 nt

; __device__ __forceinline__ unsigned cvt_pk_bf16(float lo, float hi) { unsigned r; asm volatile("v_cvt_pk_bf16_f32 %0, %1, %2" : "=v"(r) : "v"(lo), "v"(hi)); return r; }
;     __device__ __forceinline__ void operator()(const f32x4 (&acc)[2][2][4][2], const pg8::Unit& u, int wr, int wc, int fr, int fq) const {
;     ...
;                         u32x4 w; w.x = cvt_pk_bf16(v0[0], v0[1]); w.y = cvt_pk_bf16(v0[2], v0[3]); w.z = cvt_pk_bf16(v1[0], v1[1]); w.w = cvt_pk_bf16(v1[2], v1[3]);
;                         *(u32x4*)(dst + row * ld + coff + cl) = w;
.LBB0_407:
	v_lshlrev_b32_e32 v136, 1, v138
	v_lshl_add_u64 v[12:13], v[16:17], 0, v[136:137]
	v_cvt_pk_bf16_f32 v8, v20, v21
	v_cvt_pk_bf16_f32 v9, v22, v23
	v_cvt_pk_bf16_f32 v10, v24, v25
	v_cvt_pk_bf16_f32 v11, v26, v27
	global_store_dwordx4 v[12:13], v[8:11], off nt
	s_and_b64 vcc, exec, s[8:9]
	s_mov_b64 s[8:9], -1
	s_cbranch_vccz .LBB0_417

; __device__ __forceinline__ unsigned cvt_pk_bf16(float lo, float hi) { unsigned r; asm volatile("v_cvt_pk_bf16_f32 %0, %1, %2" : "=v"(r) : "v"(lo), "v"(hi)); return r; }
; template <class Epi, bool BLKDIAG = false>
; __device__ __forceinline__ void gemm_phase(PG8_LAS unsigned char* lds, const Gemm g, const StaticOrder& S, const Epi& E) {
;     ...
;         if (!has_next) break;
;     __device__ __forceinline__ void operator()(const f32x4 (&acc)[2][2][4][2], const pg8::Unit& u, int wr, int wc, int fr, int fq) const {
;     ...
;                         u32x4 w; w.x = cvt_pk_bf16(v0[0], v0[1]); w.y = cvt_pk_bf16(v0[2], v0[3]); w.z = cvt_pk_bf16(v1[0], v1[1]); w.w = cvt_pk_bf16(v1[2], v1[3]);
;                         *(u32x4*)(dst + row * ld + coff + cl) = w;
.LBB0_415:
	v_lshlrev_b32_e32 v136, 1, v138
	v_lshl_add_u64 v[4:5], v[16:17], 0, v[136:137]
	v_cvt_pk_bf16_f32 v0, v8, v9
	v_cvt_pk_bf16_f32 v1, v12, v13
	v_cvt_pk_bf16_f32 v2, v10, v11
	v_cvt_pk_bf16_f32 v3, v14, v15
	global_store_dwordx4 v[4:5], v[0:3], off offset:256 nt
	s_andn2_b64 vcc, exec, s[4:5]
	s_mov_b64 s[4:5], -1
	s_cbranch_vccnz .LBB0_132
	s_branch .LBB0_421

;     __device__ __forceinline__ void operator()(const f32x4 (&acc)[2][2][4][2], const pg8::Unit& u, int wr, int wc, int fr, int fq) const {
;     ...
;                         float* p = P.CKVF + row * 256 + cl; *(f32x4*)p = v0; *(f32x4*)(p + 4) = v1;
.LBB0_417:
	s_and_b64 vcc, exec, s[6:7]
	s_cbranch_vccnz .LBB0_419
	v_lshl_add_u64 v[8:9], v[146:147], 0, v[18:19]
	global_store_dwordx4 v[8:9], v[4:7], off nt
	global_store_dwordx4 v[8:9], v[0:3], off offset:16 nt
